# P10 rope epilogue: copy propagation removes 203 operand-packing moves (on top of the 3-row-ahead table loads)
# baseline (speedup 1.0000x reference)
.LBB0_1014:
	s_lshl_b32 s6, s6, 8
	s_add_i32 s6, s6, s90
	v_add_u32_e32 v140, s6, v182
	v_ashrrev_i32_e32 v141, 31, v140
	v_lshlrev_b32_e32 v132, 6, v140
	v_lshl_add_u64 v[142:143], v[140:141], 2, s[24:25]
	v_and_b32_e32 v190, 0x3ffc0, v132
	v_add_u32_e32 v192, 0, v140
	v_lshlrev_b32_e32 v192, 6, v192
	v_and_b32_e32 v192, 0x3ffc0, v192
	global_load_dword v193, v[142:143], off
	global_load_dwordx4 v[194:197], v192, s[22:23] offset:32
	global_load_dwordx4 v[198:201], v192, s[22:23]
	global_load_dwordx4 v[202:205], v192, s[22:23] offset:48
	global_load_dwordx4 v[206:209], v192, s[22:23] offset:16
	v_add_u32_e32 v210, 16, v140
	v_lshlrev_b32_e32 v210, 6, v210
	v_and_b32_e32 v210, 0x3ffc0, v210
	global_load_dword v211, v[142:143], off offset:64
	global_load_dwordx4 v[212:215], v210, s[22:23] offset:32
	global_load_dwordx4 v[216:219], v210, s[22:23]
	global_load_dwordx4 v[220:223], v210, s[22:23] offset:48
	global_load_dwordx4 v[224:227], v210, s[22:23] offset:16
	v_add_u32_e32 v228, 32, v140
	v_lshlrev_b32_e32 v228, 6, v228
	v_and_b32_e32 v228, 0x3ffc0, v228
	global_load_dword v229, v[142:143], off offset:128
	global_load_dwordx4 v[230:233], v228, s[22:23] offset:32
	global_load_dwordx4 v[234:237], v228, s[22:23]
	global_load_dwordx4 v[238:241], v228, s[22:23] offset:48
	global_load_dwordx4 v[242:245], v228, s[22:23] offset:16
	v_and_b32_e32 v145, 64, v180
	s_add_i32 s6, s7, s91
	v_xor_b32_e32 v132, 16, v180
	v_add_u32_e32 v155, 64, v145
	v_lshl_add_u32 v144, v181, 3, s6
	v_cmp_lt_i32_e64 s[6:7], v132, v155
	s_and_b64 s[62:63], s[38:39], s[66:67]
	s_nop 0
	v_cndmask_b32_e64 v132, v180, v132, s[6:7]
	v_lshlrev_b32_e32 v132, 2, v132
	ds_bpermute_b32 v155, v132, v120
	ds_bpermute_b32 v168, v132, v126
	ds_bpermute_b32 v157, v132, v121
	ds_bpermute_b32 v159, v132, v122
	ds_bpermute_b32 v161, v132, v123
	ds_bpermute_b32 v165, v132, v125
	v_mad_i64_i32 v[166:167], s[6:7], s60, v140, 0
	ds_bpermute_b32 v163, v132, v124
	v_cmp_eq_u32_e64 s[6:7], 0, v181
	v_cmp_gt_i32_e32 vcc, 2, v181
	s_waitcnt lgkmcnt(0)
	v_cndmask_b32_e64 v169, v155, -v155, s[6:7]
	v_cndmask_b32_e64 v189, v168, -v168, s[6:7]
	v_cndmask_b32_e64 v171, v157, -v157, s[6:7]
	ds_bpermute_b32 v191, v132, v127
	v_cndmask_b32_e64 v173, v159, -v159, s[6:7]
	v_cndmask_b32_e64 v183, v161, -v161, s[6:7]
	v_cndmask_b32_e64 v187, v165, -v165, s[6:7]
	s_and_b64 vcc, s[62:63], vcc
	v_ashrrev_i32_e32 v145, 31, v144
	v_cndmask_b32_e64 v185, v163, -v163, s[6:7]
	v_lshl_add_u64 v[144:145], v[144:145], 1, s[64:65]
	v_lshl_add_u64 v[166:167], v[166:167], 1, v[144:145]
	s_waitcnt vmcnt(10)
	v_mul_f32_e32 v141, s53, v193
	v_mul_f32_e32 v150, v194, v169
	v_mul_f32_e32 v154, v195, v171
	v_fma_f32 v148, v120, v198, v150
	v_mul_f32_e32 v156, v196, v173
	v_mul_f32_e32 v158, v197, v183
	v_fma_f32 v150, v121, v199, v154
	v_cndmask_b32_e32 v120, v120, v148, vcc
	v_mul_f32_e32 v160, v194, v185
	v_mul_f32_e32 v146, v195, v187
	v_mul_f32_e32 v162, v196, v189
	v_fma_f32 v151, v122, v200, v156
	v_fma_f32 v152, v123, v201, v158
	v_cndmask_b32_e32 v121, v121, v150, vcc
	v_mul_f32_e32 v120, v141, v120
	v_fma_f32 v146, v125, v199, v146
	v_fma_f32 v147, v126, v200, v162
	v_cndmask_b32_e32 v122, v122, v151, vcc
	v_cndmask_b32_e32 v123, v123, v152, vcc
	v_mul_f32_e32 v121, v141, v121
	v_cvt_pk_bf16_f32 v120, v120, v121
	v_mul_f32_e32 v122, v141, v122
	v_mul_f32_e32 v123, v141, v123
	v_cvt_pk_bf16_f32 v121, v122, v123
	global_store_dwordx2 v[166:167], v[120:121], off
	v_cndmask_b32_e32 v120, v126, v147, vcc
	v_mul_f32_e32 v122, v141, v120
	s_waitcnt lgkmcnt(0)
	v_cndmask_b32_e64 v121, v191, -v191, s[6:7]
	v_mul_f32_e32 v120, v197, v121
	v_fma_f32 v154, v124, v198, v160
	v_fma_f32 v120, v127, v201, v120
	v_cndmask_b32_e32 v120, v127, v120, vcc
	v_cndmask_b32_e32 v124, v124, v154, vcc
	v_cndmask_b32_e32 v125, v125, v146, vcc
	v_mul_f32_e32 v121, v141, v120
	v_mul_f32_e32 v124, v141, v124
	v_mul_f32_e32 v125, v141, v125
	v_cvt_pk_bf16_f32 v120, v124, v125
	v_cvt_pk_bf16_f32 v121, v122, v121
	global_store_dwordx2 v[166:167], v[120:121], off offset:256
	s_nop 0
	ds_bpermute_b32 v147, v132, v112
	ds_bpermute_b32 v149, v132, v113
	ds_bpermute_b32 v158, v132, v118
	ds_bpermute_b32 v160, v132, v119
	ds_bpermute_b32 v151, v132, v114
	ds_bpermute_b32 v153, v132, v115
	ds_bpermute_b32 v155, v132, v116
	ds_bpermute_b32 v157, v132, v117
	s_waitcnt lgkmcnt(7)
	v_cndmask_b32_e64 v159, v147, -v147, s[6:7]
	s_waitcnt lgkmcnt(6)
	v_cndmask_b32_e64 v161, v149, -v149, s[6:7]
	s_waitcnt lgkmcnt(5)
	v_cndmask_b32_e64 v173, v158, -v158, s[6:7]
	s_waitcnt lgkmcnt(4)
	v_cndmask_b32_e64 v183, v160, -v160, s[6:7]
	s_waitcnt lgkmcnt(3)
	v_cndmask_b32_e64 v163, v151, -v151, s[6:7]
	s_waitcnt lgkmcnt(2)
	v_cndmask_b32_e64 v165, v153, -v153, s[6:7]
	s_waitcnt lgkmcnt(1)
	v_cndmask_b32_e64 v169, v155, -v155, s[6:7]
	s_waitcnt lgkmcnt(0)
	v_cndmask_b32_e64 v171, v157, -v157, s[6:7]
	v_mul_f32_e32 v124, v202, v159
	v_mul_f32_e32 v126, v203, v161
	v_mul_f32_e32 v146, v204, v163
	v_mul_f32_e32 v148, v205, v165
	v_fma_f32 v124, v112, v206, v124
	v_fma_f32 v125, v113, v207, v126
	v_mul_f32_e32 v150, v202, v169
	v_mul_f32_e32 v120, v203, v171
	v_mul_f32_e32 v152, v204, v173
	v_mul_f32_e32 v122, v205, v183
	v_fma_f32 v126, v114, v208, v146
	v_fma_f32 v127, v115, v209, v148
	v_cndmask_b32_e32 v112, v112, v124, vcc
	v_cndmask_b32_e32 v113, v113, v125, vcc
	v_fma_f32 v146, v116, v206, v150
	v_fma_f32 v120, v117, v207, v120
	v_fma_f32 v121, v118, v208, v152
	v_fma_f32 v122, v119, v209, v122
	v_cndmask_b32_e32 v114, v114, v126, vcc
	v_cndmask_b32_e32 v115, v115, v127, vcc
	v_mul_f32_e32 v112, v141, v112
	v_mul_f32_e32 v113, v141, v113
	v_cndmask_b32_e32 v116, v116, v146, vcc
	v_cndmask_b32_e32 v117, v117, v120, vcc
	v_cndmask_b32_e32 v118, v118, v121, vcc
	v_cndmask_b32_e32 v119, v119, v122, vcc
	v_mul_f32_e32 v114, v141, v114
	v_mul_f32_e32 v115, v141, v115
	v_cvt_pk_bf16_f32 v112, v112, v113
	v_cvt_pk_bf16_f32 v113, v114, v115
	v_mul_f32_e32 v116, v141, v116
	v_mul_f32_e32 v117, v141, v117
	v_mul_f32_e32 v118, v141, v118
	v_mul_f32_e32 v119, v141, v119
	global_store_dwordx2 v[166:167], v[112:113], off offset:8
	v_cvt_pk_bf16_f32 v112, v116, v117
	v_cvt_pk_bf16_f32 v113, v118, v119
	global_store_dwordx2 v[166:167], v[112:113], off offset:264
	v_add_u32_e32 v192, 48, v140
	v_lshlrev_b32_e32 v192, 6, v192
	v_and_b32_e32 v192, 0x3ffc0, v192
	global_load_dword v193, v[142:143], off offset:192
	global_load_dwordx4 v[194:197], v192, s[22:23] offset:32
	global_load_dwordx4 v[198:201], v192, s[22:23]
	global_load_dwordx4 v[202:205], v192, s[22:23] offset:48
	global_load_dwordx4 v[206:209], v192, s[22:23] offset:16
	v_add_u32_e32 v121, 16, v140
	v_lshlrev_b32_e32 v112, 6, v121
	v_and_b32_e32 v141, 0x3ffc0, v112
	ds_bpermute_b32 v125, v132, v104
	ds_bpermute_b32 v127, v132, v105
	ds_bpermute_b32 v152, v132, v108
	ds_bpermute_b32 v154, v132, v109
	ds_bpermute_b32 v147, v132, v106
	ds_bpermute_b32 v149, v132, v107
	ds_bpermute_b32 v156, v132, v110
	ds_bpermute_b32 v158, v132, v111
	v_mad_i64_i32 v[150:151], s[62:63], s60, v121, 0
	s_waitcnt lgkmcnt(7)
	v_cndmask_b32_e64 v153, v125, -v125, s[6:7]
	s_waitcnt lgkmcnt(6)
	v_cndmask_b32_e64 v155, v127, -v127, s[6:7]
	s_waitcnt lgkmcnt(5)
	v_cndmask_b32_e64 v161, v152, -v152, s[6:7]
	s_waitcnt lgkmcnt(4)
	v_cndmask_b32_e64 v163, v154, -v154, s[6:7]
	s_waitcnt lgkmcnt(3)
	v_cndmask_b32_e64 v157, v147, -v147, s[6:7]
	s_waitcnt lgkmcnt(2)
	v_cndmask_b32_e64 v159, v149, -v149, s[6:7]
	s_waitcnt lgkmcnt(1)
	v_cndmask_b32_e64 v165, v156, -v156, s[6:7]
	s_waitcnt lgkmcnt(0)
	v_cndmask_b32_e64 v167, v158, -v158, s[6:7]
	v_lshl_add_u64 v[150:151], v[150:151], 1, v[144:145]
	s_waitcnt vmcnt(14)
	v_mul_f32_e32 v168, s53, v211
	v_mul_f32_e32 v116, v212, v153
	v_mul_f32_e32 v118, v213, v155
	v_mul_f32_e32 v120, v214, v157
	v_mul_f32_e32 v122, v215, v159
	v_fma_f32 v116, v104, v216, v116
	v_fma_f32 v117, v105, v217, v118
	v_mul_f32_e32 v124, v212, v161
	v_mul_f32_e32 v112, v213, v163
	v_mul_f32_e32 v126, v214, v165
	v_mul_f32_e32 v114, v215, v167
	v_fma_f32 v118, v106, v218, v120
	v_fma_f32 v119, v107, v219, v122
	v_cndmask_b32_e32 v104, v104, v116, vcc
	v_cndmask_b32_e32 v105, v105, v117, vcc
	v_fma_f32 v120, v108, v216, v124
	v_fma_f32 v112, v109, v217, v112
	v_fma_f32 v113, v110, v218, v126
	v_fma_f32 v114, v111, v219, v114
	v_cndmask_b32_e32 v106, v106, v118, vcc
	v_cndmask_b32_e32 v107, v107, v119, vcc
	v_mul_f32_e32 v104, v168, v104
	v_mul_f32_e32 v105, v168, v105
	v_cndmask_b32_e32 v108, v108, v120, vcc
	v_cndmask_b32_e32 v109, v109, v112, vcc
	v_cndmask_b32_e32 v110, v110, v113, vcc
	v_cndmask_b32_e32 v111, v111, v114, vcc
	v_mul_f32_e32 v106, v168, v106
	v_mul_f32_e32 v107, v168, v107
	v_cvt_pk_bf16_f32 v104, v104, v105
	v_cvt_pk_bf16_f32 v105, v106, v107
	v_mul_f32_e32 v108, v168, v108
	v_mul_f32_e32 v109, v168, v109
	v_mul_f32_e32 v110, v168, v110
	v_mul_f32_e32 v111, v168, v111
	global_store_dwordx2 v[150:151], v[104:105], off
	v_cvt_pk_bf16_f32 v104, v108, v109
	v_cvt_pk_bf16_f32 v105, v110, v111
	global_store_dwordx2 v[150:151], v[104:105], off offset:256
	s_nop 0
	ds_bpermute_b32 v113, v132, v96
	ds_bpermute_b32 v115, v132, v97
	ds_bpermute_b32 v124, v132, v102
	ds_bpermute_b32 v126, v132, v103
	ds_bpermute_b32 v117, v132, v98
	ds_bpermute_b32 v119, v132, v99
	ds_bpermute_b32 v121, v132, v100
	ds_bpermute_b32 v123, v132, v101
	s_waitcnt lgkmcnt(7)
	v_cndmask_b32_e64 v125, v113, -v113, s[6:7]
	s_waitcnt lgkmcnt(6)
	v_cndmask_b32_e64 v127, v115, -v115, s[6:7]
	s_waitcnt lgkmcnt(5)
	v_cndmask_b32_e64 v157, v124, -v124, s[6:7]
	s_waitcnt lgkmcnt(4)
	v_cndmask_b32_e64 v159, v126, -v126, s[6:7]
	s_waitcnt lgkmcnt(3)
	v_cndmask_b32_e64 v147, v117, -v117, s[6:7]
	s_waitcnt lgkmcnt(2)
	v_cndmask_b32_e64 v149, v119, -v119, s[6:7]
	s_waitcnt lgkmcnt(1)
	v_cndmask_b32_e64 v153, v121, -v121, s[6:7]
	s_waitcnt lgkmcnt(0)
	v_cndmask_b32_e64 v155, v123, -v123, s[6:7]
	v_mul_f32_e32 v108, v220, v125
	v_mul_f32_e32 v110, v221, v127
	v_mul_f32_e32 v112, v222, v147
	v_mul_f32_e32 v114, v223, v149
	v_fma_f32 v108, v96, v224, v108
	v_fma_f32 v109, v97, v225, v110
	v_mul_f32_e32 v116, v220, v153
	v_mul_f32_e32 v104, v221, v155
	v_mul_f32_e32 v118, v222, v157
	v_mul_f32_e32 v106, v223, v159
	v_fma_f32 v110, v98, v226, v112
	v_fma_f32 v111, v99, v227, v114
	v_cndmask_b32_e32 v96, v96, v108, vcc
	v_cndmask_b32_e32 v97, v97, v109, vcc
	v_fma_f32 v112, v100, v224, v116
	v_fma_f32 v104, v101, v225, v104
	v_fma_f32 v105, v102, v226, v118
	v_fma_f32 v106, v103, v227, v106
	v_cndmask_b32_e32 v98, v98, v110, vcc
	v_cndmask_b32_e32 v99, v99, v111, vcc
	v_mul_f32_e32 v96, v168, v96
	v_mul_f32_e32 v97, v168, v97
	v_cndmask_b32_e32 v100, v100, v112, vcc
	v_cndmask_b32_e32 v101, v101, v104, vcc
	v_cndmask_b32_e32 v102, v102, v105, vcc
	v_cndmask_b32_e32 v103, v103, v106, vcc
	v_mul_f32_e32 v98, v168, v98
	v_mul_f32_e32 v99, v168, v99
	v_cvt_pk_bf16_f32 v96, v96, v97
	v_cvt_pk_bf16_f32 v97, v98, v99
	v_mul_f32_e32 v100, v168, v100
	v_mul_f32_e32 v101, v168, v101
	v_mul_f32_e32 v102, v168, v102
	v_mul_f32_e32 v103, v168, v103
	global_store_dwordx2 v[150:151], v[96:97], off offset:8
	v_cvt_pk_bf16_f32 v96, v100, v101
	v_cvt_pk_bf16_f32 v97, v102, v103
	global_store_dwordx2 v[150:151], v[96:97], off offset:264
	v_add_u32_e32 v210, 128, v140
	v_lshlrev_b32_e32 v210, 6, v210
	v_and_b32_e32 v210, 0x3ffc0, v210
	global_load_dword v211, v[142:143], off offset:512
	global_load_dwordx4 v[212:215], v210, s[22:23] offset:32
	global_load_dwordx4 v[216:219], v210, s[22:23]
	global_load_dwordx4 v[220:223], v210, s[22:23] offset:48
	global_load_dwordx4 v[224:227], v210, s[22:23] offset:16
	v_add_u32_e32 v105, 32, v140
	v_lshlrev_b32_e32 v96, 6, v105
	v_and_b32_e32 v141, 0x3ffc0, v96
	ds_bpermute_b32 v109, v132, v88
	ds_bpermute_b32 v111, v132, v89
	ds_bpermute_b32 v118, v132, v92
	ds_bpermute_b32 v120, v132, v93
	ds_bpermute_b32 v113, v132, v90
	ds_bpermute_b32 v115, v132, v91
	ds_bpermute_b32 v122, v132, v94
	ds_bpermute_b32 v124, v132, v95
	v_mad_i64_i32 v[116:117], s[62:63], s60, v105, 0
	s_waitcnt lgkmcnt(7)
	v_cndmask_b32_e64 v119, v109, -v109, s[6:7]
	s_waitcnt lgkmcnt(6)
	v_cndmask_b32_e64 v121, v111, -v111, s[6:7]
	s_waitcnt lgkmcnt(5)
	v_cndmask_b32_e64 v127, v118, -v118, s[6:7]
	s_waitcnt lgkmcnt(4)
	v_cndmask_b32_e64 v147, v120, -v120, s[6:7]
	s_waitcnt lgkmcnt(3)
	v_cndmask_b32_e64 v123, v113, -v113, s[6:7]
	s_waitcnt lgkmcnt(2)
	v_cndmask_b32_e64 v125, v115, -v115, s[6:7]
	s_waitcnt lgkmcnt(1)
	v_cndmask_b32_e64 v149, v122, -v122, s[6:7]
	s_waitcnt lgkmcnt(0)
	v_cndmask_b32_e64 v151, v124, -v124, s[6:7]
	v_lshl_add_u64 v[116:117], v[116:117], 1, v[144:145]
	s_waitcnt vmcnt(18)
	v_mul_f32_e32 v152, s53, v229
	v_mul_f32_e32 v100, v230, v119
	v_mul_f32_e32 v102, v231, v121
	v_mul_f32_e32 v104, v232, v123
	v_mul_f32_e32 v106, v233, v125
	v_fma_f32 v100, v88, v234, v100
	v_fma_f32 v101, v89, v235, v102
	v_mul_f32_e32 v108, v230, v127
	v_mul_f32_e32 v96, v231, v147
	v_mul_f32_e32 v110, v232, v149
	v_mul_f32_e32 v98, v233, v151
	v_fma_f32 v102, v90, v236, v104
	v_fma_f32 v103, v91, v237, v106
	v_cndmask_b32_e32 v88, v88, v100, vcc
	v_cndmask_b32_e32 v89, v89, v101, vcc
	v_fma_f32 v104, v92, v234, v108
	v_fma_f32 v96, v93, v235, v96
	v_fma_f32 v97, v94, v236, v110
	v_fma_f32 v98, v95, v237, v98
	v_cndmask_b32_e32 v90, v90, v102, vcc
	v_cndmask_b32_e32 v91, v91, v103, vcc
	v_mul_f32_e32 v88, v152, v88
	v_mul_f32_e32 v89, v152, v89
	v_cndmask_b32_e32 v92, v92, v104, vcc
	v_cndmask_b32_e32 v93, v93, v96, vcc
	v_cndmask_b32_e32 v94, v94, v97, vcc
	v_cndmask_b32_e32 v95, v95, v98, vcc
	v_mul_f32_e32 v90, v152, v90
	v_mul_f32_e32 v91, v152, v91
	v_cvt_pk_bf16_f32 v88, v88, v89
	v_cvt_pk_bf16_f32 v89, v90, v91
	v_mul_f32_e32 v92, v152, v92
	v_mul_f32_e32 v93, v152, v93
	v_mul_f32_e32 v94, v152, v94
	v_mul_f32_e32 v95, v152, v95
	global_store_dwordx2 v[116:117], v[88:89], off
	v_cvt_pk_bf16_f32 v88, v92, v93
	v_cvt_pk_bf16_f32 v89, v94, v95
	global_store_dwordx2 v[116:117], v[88:89], off offset:256
	s_nop 0
	ds_bpermute_b32 v97, v132, v80
	ds_bpermute_b32 v99, v132, v81
	ds_bpermute_b32 v108, v132, v86
	ds_bpermute_b32 v110, v132, v87
	ds_bpermute_b32 v101, v132, v82
	ds_bpermute_b32 v103, v132, v83
	ds_bpermute_b32 v105, v132, v84
	ds_bpermute_b32 v107, v132, v85
	s_waitcnt lgkmcnt(7)
	v_cndmask_b32_e64 v109, v97, -v97, s[6:7]
	s_waitcnt lgkmcnt(6)
	v_cndmask_b32_e64 v111, v99, -v99, s[6:7]
	s_waitcnt lgkmcnt(5)
	v_cndmask_b32_e64 v123, v108, -v108, s[6:7]
	s_waitcnt lgkmcnt(4)
	v_cndmask_b32_e64 v125, v110, -v110, s[6:7]
	s_waitcnt lgkmcnt(3)
	v_cndmask_b32_e64 v113, v101, -v101, s[6:7]
	s_waitcnt lgkmcnt(2)
	v_cndmask_b32_e64 v115, v103, -v103, s[6:7]
	s_waitcnt lgkmcnt(1)
	v_cndmask_b32_e64 v119, v105, -v105, s[6:7]
	s_waitcnt lgkmcnt(0)
	v_cndmask_b32_e64 v121, v107, -v107, s[6:7]
	v_mul_f32_e32 v92, v238, v109
	v_mul_f32_e32 v94, v239, v111
	v_mul_f32_e32 v96, v240, v113
	v_mul_f32_e32 v98, v241, v115
	v_fma_f32 v92, v80, v242, v92
	v_fma_f32 v93, v81, v243, v94
	v_mul_f32_e32 v100, v238, v119
	v_mul_f32_e32 v88, v239, v121
	v_mul_f32_e32 v102, v240, v123
	v_mul_f32_e32 v90, v241, v125
	v_fma_f32 v94, v82, v244, v96
	v_fma_f32 v95, v83, v245, v98
	v_cndmask_b32_e32 v80, v80, v92, vcc
	v_cndmask_b32_e32 v81, v81, v93, vcc
	v_fma_f32 v96, v84, v242, v100
	v_fma_f32 v88, v85, v243, v88
	v_fma_f32 v89, v86, v244, v102
	v_fma_f32 v90, v87, v245, v90
	v_cndmask_b32_e32 v82, v82, v94, vcc
	v_cndmask_b32_e32 v83, v83, v95, vcc
	v_mul_f32_e32 v80, v152, v80
	v_mul_f32_e32 v81, v152, v81
	v_cndmask_b32_e32 v84, v84, v96, vcc
	v_cndmask_b32_e32 v85, v85, v88, vcc
	v_cndmask_b32_e32 v86, v86, v89, vcc
	v_cndmask_b32_e32 v87, v87, v90, vcc
	v_mul_f32_e32 v82, v152, v82
	v_mul_f32_e32 v83, v152, v83
	v_cvt_pk_bf16_f32 v80, v80, v81
	v_cvt_pk_bf16_f32 v81, v82, v83
	v_mul_f32_e32 v84, v152, v84
	v_mul_f32_e32 v85, v152, v85
	v_mul_f32_e32 v86, v152, v86
	v_mul_f32_e32 v87, v152, v87
	global_store_dwordx2 v[116:117], v[80:81], off offset:8
	v_cvt_pk_bf16_f32 v80, v84, v85
	v_cvt_pk_bf16_f32 v81, v86, v87
	global_store_dwordx2 v[116:117], v[80:81], off offset:264
	v_add_u32_e32 v228, 144, v140
	v_lshlrev_b32_e32 v228, 6, v228
	v_and_b32_e32 v228, 0x3ffc0, v228
	global_load_dword v229, v[142:143], off offset:576
	global_load_dwordx4 v[230:233], v228, s[22:23] offset:32
	global_load_dwordx4 v[234:237], v228, s[22:23]
	global_load_dwordx4 v[238:241], v228, s[22:23] offset:48
	global_load_dwordx4 v[242:245], v228, s[22:23] offset:16
	v_add_u32_e32 v89, 48, v140
	v_lshlrev_b32_e32 v80, 6, v89
	v_and_b32_e32 v118, 0x3ffc0, v80
	ds_bpermute_b32 v93, v132, v72
	ds_bpermute_b32 v95, v132, v73
	ds_bpermute_b32 v102, v132, v76
	ds_bpermute_b32 v104, v132, v77
	ds_bpermute_b32 v97, v132, v74
	ds_bpermute_b32 v99, v132, v75
	ds_bpermute_b32 v106, v132, v78
	ds_bpermute_b32 v108, v132, v79
	v_mad_i64_i32 v[100:101], s[62:63], s60, v89, 0
	s_waitcnt lgkmcnt(7)
	v_cndmask_b32_e64 v103, v93, -v93, s[6:7]
	s_waitcnt lgkmcnt(6)
	v_cndmask_b32_e64 v105, v95, -v95, s[6:7]
	s_waitcnt lgkmcnt(5)
	v_cndmask_b32_e64 v111, v102, -v102, s[6:7]
	s_waitcnt lgkmcnt(4)
	v_cndmask_b32_e64 v113, v104, -v104, s[6:7]
	s_waitcnt lgkmcnt(3)
	v_cndmask_b32_e64 v107, v97, -v97, s[6:7]
	s_waitcnt lgkmcnt(2)
	v_cndmask_b32_e64 v109, v99, -v99, s[6:7]
	s_waitcnt lgkmcnt(1)
	v_cndmask_b32_e64 v115, v106, -v106, s[6:7]
	s_waitcnt lgkmcnt(0)
	v_cndmask_b32_e64 v117, v108, -v108, s[6:7]
	v_lshl_add_u64 v[100:101], v[100:101], 1, v[144:145]
	s_waitcnt vmcnt(18)
	v_mul_f32_e32 v119, s53, v193
	v_mul_f32_e32 v84, v194, v103
	v_mul_f32_e32 v86, v195, v105
	v_mul_f32_e32 v88, v196, v107
	v_mul_f32_e32 v90, v197, v109
	v_fma_f32 v84, v72, v198, v84
	v_fma_f32 v85, v73, v199, v86
	v_mul_f32_e32 v92, v194, v111
	v_mul_f32_e32 v80, v195, v113
	v_mul_f32_e32 v94, v196, v115
	v_mul_f32_e32 v82, v197, v117
	v_fma_f32 v86, v74, v200, v88
	v_fma_f32 v87, v75, v201, v90
	v_cndmask_b32_e32 v72, v72, v84, vcc
	v_cndmask_b32_e32 v73, v73, v85, vcc
	v_fma_f32 v88, v76, v198, v92
	v_fma_f32 v80, v77, v199, v80
	v_fma_f32 v81, v78, v200, v94
	v_fma_f32 v82, v79, v201, v82
	v_cndmask_b32_e32 v74, v74, v86, vcc
	v_cndmask_b32_e32 v75, v75, v87, vcc
	v_mul_f32_e32 v72, v119, v72
	v_mul_f32_e32 v73, v119, v73
	v_cndmask_b32_e32 v76, v76, v88, vcc
	v_cndmask_b32_e32 v77, v77, v80, vcc
	v_cndmask_b32_e32 v78, v78, v81, vcc
	v_cndmask_b32_e32 v79, v79, v82, vcc
	v_mul_f32_e32 v74, v119, v74
	v_mul_f32_e32 v75, v119, v75
	v_cvt_pk_bf16_f32 v72, v72, v73
	v_cvt_pk_bf16_f32 v73, v74, v75
	v_mul_f32_e32 v76, v119, v76
	v_mul_f32_e32 v77, v119, v77
	v_mul_f32_e32 v78, v119, v78
	v_mul_f32_e32 v79, v119, v79
	global_store_dwordx2 v[100:101], v[72:73], off
	v_cvt_pk_bf16_f32 v72, v76, v77
	v_cvt_pk_bf16_f32 v73, v78, v79
	global_store_dwordx2 v[100:101], v[72:73], off offset:256
	s_nop 0
	ds_bpermute_b32 v81, v132, v64
	ds_bpermute_b32 v83, v132, v65
	ds_bpermute_b32 v92, v132, v70
	ds_bpermute_b32 v94, v132, v71
	ds_bpermute_b32 v85, v132, v66
	ds_bpermute_b32 v87, v132, v67
	ds_bpermute_b32 v89, v132, v68
	ds_bpermute_b32 v91, v132, v69
	s_waitcnt lgkmcnt(7)
	v_cndmask_b32_e64 v93, v81, -v81, s[6:7]
	s_waitcnt lgkmcnt(6)
	v_cndmask_b32_e64 v95, v83, -v83, s[6:7]
	s_waitcnt lgkmcnt(5)
	v_cndmask_b32_e64 v107, v92, -v92, s[6:7]
	s_waitcnt lgkmcnt(4)
	v_cndmask_b32_e64 v109, v94, -v94, s[6:7]
	s_waitcnt lgkmcnt(3)
	v_cndmask_b32_e64 v97, v85, -v85, s[6:7]
	s_waitcnt lgkmcnt(2)
	v_cndmask_b32_e64 v99, v87, -v87, s[6:7]
	s_waitcnt lgkmcnt(1)
	v_cndmask_b32_e64 v103, v89, -v89, s[6:7]
	s_waitcnt lgkmcnt(0)
	v_cndmask_b32_e64 v105, v91, -v91, s[6:7]
	v_mul_f32_e32 v76, v202, v93
	v_mul_f32_e32 v78, v203, v95
	v_mul_f32_e32 v80, v204, v97
	v_mul_f32_e32 v82, v205, v99
	v_fma_f32 v76, v64, v206, v76
	v_fma_f32 v77, v65, v207, v78
	v_mul_f32_e32 v84, v202, v103
	v_mul_f32_e32 v72, v203, v105
	v_mul_f32_e32 v86, v204, v107
	v_mul_f32_e32 v74, v205, v109
	v_fma_f32 v78, v66, v208, v80
	v_fma_f32 v79, v67, v209, v82
	v_cndmask_b32_e32 v64, v64, v76, vcc
	v_cndmask_b32_e32 v65, v65, v77, vcc
	v_fma_f32 v80, v68, v206, v84
	v_fma_f32 v72, v69, v207, v72
	v_fma_f32 v73, v70, v208, v86
	v_fma_f32 v74, v71, v209, v74
	v_cndmask_b32_e32 v66, v66, v78, vcc
	v_cndmask_b32_e32 v67, v67, v79, vcc
	v_mul_f32_e32 v64, v119, v64
	v_mul_f32_e32 v65, v119, v65
	v_cndmask_b32_e32 v68, v68, v80, vcc
	v_cndmask_b32_e32 v69, v69, v72, vcc
	v_cndmask_b32_e32 v70, v70, v73, vcc
	v_cndmask_b32_e32 v71, v71, v74, vcc
	v_mul_f32_e32 v66, v119, v66
	v_mul_f32_e32 v67, v119, v67
	v_cvt_pk_bf16_f32 v64, v64, v65
	v_cvt_pk_bf16_f32 v65, v66, v67
	v_mul_f32_e32 v68, v119, v68
	v_mul_f32_e32 v69, v119, v69
	v_mul_f32_e32 v70, v119, v70
	v_mul_f32_e32 v71, v119, v71
	global_store_dwordx2 v[100:101], v[64:65], off offset:8
	v_cvt_pk_bf16_f32 v64, v68, v69
	v_cvt_pk_bf16_f32 v65, v70, v71
	global_store_dwordx2 v[100:101], v[64:65], off offset:264
	v_add_u32_e32 v192, 160, v140
	v_lshlrev_b32_e32 v192, 6, v192
	v_and_b32_e32 v192, 0x3ffc0, v192
	global_load_dword v193, v[142:143], off offset:640
	global_load_dwordx4 v[194:197], v192, s[22:23] offset:32
	global_load_dwordx4 v[198:201], v192, s[22:23]
	global_load_dwordx4 v[202:205], v192, s[22:23] offset:48
	global_load_dwordx4 v[206:209], v192, s[22:23] offset:16
	v_add_u32_e32 v73, 0x80, v140
	v_lshlrev_b32_e32 v64, 6, v73
	v_and_b32_e32 v102, 0x3ffc0, v64
	ds_bpermute_b32 v77, v132, v56
	ds_bpermute_b32 v79, v132, v57
	ds_bpermute_b32 v86, v132, v60
	ds_bpermute_b32 v88, v132, v61
	ds_bpermute_b32 v81, v132, v58
	ds_bpermute_b32 v83, v132, v59
	ds_bpermute_b32 v90, v132, v62
	ds_bpermute_b32 v92, v132, v63
	v_mad_i64_i32 v[84:85], s[62:63], s60, v73, 0
	s_waitcnt lgkmcnt(7)
	v_cndmask_b32_e64 v87, v77, -v77, s[6:7]
	s_waitcnt lgkmcnt(6)
	v_cndmask_b32_e64 v89, v79, -v79, s[6:7]
	s_waitcnt lgkmcnt(5)
	v_cndmask_b32_e64 v95, v86, -v86, s[6:7]
	s_waitcnt lgkmcnt(4)
	v_cndmask_b32_e64 v97, v88, -v88, s[6:7]
	s_waitcnt lgkmcnt(3)
	v_cndmask_b32_e64 v91, v81, -v81, s[6:7]
	s_waitcnt lgkmcnt(2)
	v_cndmask_b32_e64 v93, v83, -v83, s[6:7]
	s_waitcnt lgkmcnt(1)
	v_cndmask_b32_e64 v99, v90, -v90, s[6:7]
	s_waitcnt lgkmcnt(0)
	v_cndmask_b32_e64 v101, v92, -v92, s[6:7]
	v_lshl_add_u64 v[84:85], v[84:85], 1, v[144:145]
	s_waitcnt vmcnt(18)
	v_mul_f32_e32 v103, s53, v211
	v_mul_f32_e32 v68, v212, v87
	v_mul_f32_e32 v70, v213, v89
	v_mul_f32_e32 v72, v214, v91
	v_mul_f32_e32 v74, v215, v93
	v_fma_f32 v68, v56, v216, v68
	v_fma_f32 v69, v57, v217, v70
	v_mul_f32_e32 v76, v212, v95
	v_mul_f32_e32 v64, v213, v97
	v_mul_f32_e32 v78, v214, v99
	v_mul_f32_e32 v66, v215, v101
	v_fma_f32 v70, v58, v218, v72
	v_fma_f32 v71, v59, v219, v74
	v_cndmask_b32_e32 v56, v56, v68, vcc
	v_cndmask_b32_e32 v57, v57, v69, vcc
	v_fma_f32 v72, v60, v216, v76
	v_fma_f32 v64, v61, v217, v64
	v_fma_f32 v65, v62, v218, v78
	v_fma_f32 v66, v63, v219, v66
	v_cndmask_b32_e32 v58, v58, v70, vcc
	v_cndmask_b32_e32 v59, v59, v71, vcc
	v_mul_f32_e32 v56, v103, v56
	v_mul_f32_e32 v57, v103, v57
	v_cndmask_b32_e32 v60, v60, v72, vcc
	v_cndmask_b32_e32 v61, v61, v64, vcc
	v_cndmask_b32_e32 v62, v62, v65, vcc
	v_cndmask_b32_e32 v63, v63, v66, vcc
	v_mul_f32_e32 v58, v103, v58
	v_mul_f32_e32 v59, v103, v59
	v_cvt_pk_bf16_f32 v56, v56, v57
	v_cvt_pk_bf16_f32 v57, v58, v59
	v_mul_f32_e32 v60, v103, v60
	v_mul_f32_e32 v61, v103, v61
	v_mul_f32_e32 v62, v103, v62
	v_mul_f32_e32 v63, v103, v63
	global_store_dwordx2 v[84:85], v[56:57], off
	v_cvt_pk_bf16_f32 v56, v60, v61
	v_cvt_pk_bf16_f32 v57, v62, v63
	global_store_dwordx2 v[84:85], v[56:57], off offset:256
	s_nop 0
	ds_bpermute_b32 v65, v132, v48
	ds_bpermute_b32 v67, v132, v49
	ds_bpermute_b32 v76, v132, v54
	ds_bpermute_b32 v78, v132, v55
	ds_bpermute_b32 v69, v132, v50
	ds_bpermute_b32 v71, v132, v51
	ds_bpermute_b32 v73, v132, v52
	ds_bpermute_b32 v75, v132, v53
	s_waitcnt lgkmcnt(7)
	v_cndmask_b32_e64 v77, v65, -v65, s[6:7]
	s_waitcnt lgkmcnt(6)
	v_cndmask_b32_e64 v79, v67, -v67, s[6:7]
	s_waitcnt lgkmcnt(5)
	v_cndmask_b32_e64 v91, v76, -v76, s[6:7]
	s_waitcnt lgkmcnt(4)
	v_cndmask_b32_e64 v93, v78, -v78, s[6:7]
	s_waitcnt lgkmcnt(3)
	v_cndmask_b32_e64 v81, v69, -v69, s[6:7]
	s_waitcnt lgkmcnt(2)
	v_cndmask_b32_e64 v83, v71, -v71, s[6:7]
	s_waitcnt lgkmcnt(1)
	v_cndmask_b32_e64 v87, v73, -v73, s[6:7]
	s_waitcnt lgkmcnt(0)
	v_cndmask_b32_e64 v89, v75, -v75, s[6:7]
	v_mul_f32_e32 v60, v220, v77
	v_mul_f32_e32 v62, v221, v79
	v_mul_f32_e32 v64, v222, v81
	v_mul_f32_e32 v66, v223, v83
	v_fma_f32 v60, v48, v224, v60
	v_fma_f32 v61, v49, v225, v62
	v_mul_f32_e32 v68, v220, v87
	v_mul_f32_e32 v56, v221, v89
	v_mul_f32_e32 v70, v222, v91
	v_mul_f32_e32 v58, v223, v93
	v_fma_f32 v62, v50, v226, v64
	v_fma_f32 v63, v51, v227, v66
	v_cndmask_b32_e32 v48, v48, v60, vcc
	v_cndmask_b32_e32 v49, v49, v61, vcc
	v_fma_f32 v64, v52, v224, v68
	v_fma_f32 v56, v53, v225, v56
	v_fma_f32 v57, v54, v226, v70
	v_fma_f32 v58, v55, v227, v58
	v_cndmask_b32_e32 v50, v50, v62, vcc
	v_cndmask_b32_e32 v51, v51, v63, vcc
	v_mul_f32_e32 v48, v103, v48
	v_mul_f32_e32 v49, v103, v49
	v_cndmask_b32_e32 v52, v52, v64, vcc
	v_cndmask_b32_e32 v53, v53, v56, vcc
	v_cndmask_b32_e32 v54, v54, v57, vcc
	v_cndmask_b32_e32 v55, v55, v58, vcc
	v_mul_f32_e32 v50, v103, v50
	v_mul_f32_e32 v51, v103, v51
	v_cvt_pk_bf16_f32 v48, v48, v49
	v_cvt_pk_bf16_f32 v49, v50, v51
	v_mul_f32_e32 v52, v103, v52
	v_mul_f32_e32 v53, v103, v53
	v_mul_f32_e32 v54, v103, v54
	v_mul_f32_e32 v55, v103, v55
	global_store_dwordx2 v[84:85], v[48:49], off offset:8
	v_cvt_pk_bf16_f32 v48, v52, v53
	v_cvt_pk_bf16_f32 v49, v54, v55
	global_store_dwordx2 v[84:85], v[48:49], off offset:264
	v_add_u32_e32 v210, 176, v140
	v_lshlrev_b32_e32 v210, 6, v210
	v_and_b32_e32 v210, 0x3ffc0, v210
	global_load_dword v211, v[142:143], off offset:704
	global_load_dwordx4 v[212:215], v210, s[22:23] offset:32
	global_load_dwordx4 v[216:219], v210, s[22:23]
	global_load_dwordx4 v[220:223], v210, s[22:23] offset:48
	global_load_dwordx4 v[224:227], v210, s[22:23] offset:16
	v_add_u32_e32 v57, 0x90, v140
	v_lshlrev_b32_e32 v48, 6, v57
	v_and_b32_e32 v86, 0x3ffc0, v48
	ds_bpermute_b32 v61, v132, v40
	ds_bpermute_b32 v63, v132, v41
	ds_bpermute_b32 v70, v132, v44
	ds_bpermute_b32 v72, v132, v45
	ds_bpermute_b32 v65, v132, v42
	ds_bpermute_b32 v67, v132, v43
	ds_bpermute_b32 v74, v132, v46
	ds_bpermute_b32 v76, v132, v47
	v_mad_i64_i32 v[68:69], s[62:63], s60, v57, 0
	s_waitcnt lgkmcnt(7)
	v_cndmask_b32_e64 v71, v61, -v61, s[6:7]
	s_waitcnt lgkmcnt(6)
	v_cndmask_b32_e64 v73, v63, -v63, s[6:7]
	s_waitcnt lgkmcnt(5)
	v_cndmask_b32_e64 v79, v70, -v70, s[6:7]
	s_waitcnt lgkmcnt(4)
	v_cndmask_b32_e64 v81, v72, -v72, s[6:7]
	s_waitcnt lgkmcnt(3)
	v_cndmask_b32_e64 v75, v65, -v65, s[6:7]
	s_waitcnt lgkmcnt(2)
	v_cndmask_b32_e64 v77, v67, -v67, s[6:7]
	s_waitcnt lgkmcnt(1)
	v_cndmask_b32_e64 v83, v74, -v74, s[6:7]
	s_waitcnt lgkmcnt(0)
	v_cndmask_b32_e64 v85, v76, -v76, s[6:7]
	v_lshl_add_u64 v[68:69], v[68:69], 1, v[144:145]
	s_waitcnt vmcnt(18)
	v_mul_f32_e32 v87, s53, v229
	v_mul_f32_e32 v52, v230, v71
	v_mul_f32_e32 v54, v231, v73
	v_mul_f32_e32 v56, v232, v75
	v_mul_f32_e32 v58, v233, v77
	v_fma_f32 v52, v40, v234, v52
	v_fma_f32 v53, v41, v235, v54
	v_mul_f32_e32 v60, v230, v79
	v_mul_f32_e32 v48, v231, v81
	v_mul_f32_e32 v62, v232, v83
	v_mul_f32_e32 v50, v233, v85
	v_fma_f32 v54, v42, v236, v56
	v_fma_f32 v55, v43, v237, v58
	v_cndmask_b32_e32 v40, v40, v52, vcc
	v_cndmask_b32_e32 v41, v41, v53, vcc
	v_fma_f32 v56, v44, v234, v60
	v_fma_f32 v48, v45, v235, v48
	v_fma_f32 v49, v46, v236, v62
	v_fma_f32 v50, v47, v237, v50
	v_cndmask_b32_e32 v42, v42, v54, vcc
	v_cndmask_b32_e32 v43, v43, v55, vcc
	v_mul_f32_e32 v40, v87, v40
	v_mul_f32_e32 v41, v87, v41
	v_cndmask_b32_e32 v44, v44, v56, vcc
	v_cndmask_b32_e32 v45, v45, v48, vcc
	v_cndmask_b32_e32 v46, v46, v49, vcc
	v_cndmask_b32_e32 v47, v47, v50, vcc
	v_mul_f32_e32 v42, v87, v42
	v_mul_f32_e32 v43, v87, v43
	v_cvt_pk_bf16_f32 v40, v40, v41
	v_cvt_pk_bf16_f32 v41, v42, v43
	v_mul_f32_e32 v44, v87, v44
	v_mul_f32_e32 v45, v87, v45
	v_mul_f32_e32 v46, v87, v46
	v_mul_f32_e32 v47, v87, v47
	global_store_dwordx2 v[68:69], v[40:41], off
	v_cvt_pk_bf16_f32 v40, v44, v45
	v_cvt_pk_bf16_f32 v41, v46, v47
	global_store_dwordx2 v[68:69], v[40:41], off offset:256
	s_nop 0
	ds_bpermute_b32 v49, v132, v32
	ds_bpermute_b32 v51, v132, v33
	ds_bpermute_b32 v60, v132, v38
	ds_bpermute_b32 v62, v132, v39
	ds_bpermute_b32 v53, v132, v34
	ds_bpermute_b32 v55, v132, v35
	ds_bpermute_b32 v57, v132, v36
	ds_bpermute_b32 v59, v132, v37
	s_waitcnt lgkmcnt(7)
	v_cndmask_b32_e64 v61, v49, -v49, s[6:7]
	s_waitcnt lgkmcnt(6)
	v_cndmask_b32_e64 v63, v51, -v51, s[6:7]
	s_waitcnt lgkmcnt(5)
	v_cndmask_b32_e64 v75, v60, -v60, s[6:7]
	s_waitcnt lgkmcnt(4)
	v_cndmask_b32_e64 v77, v62, -v62, s[6:7]
	s_waitcnt lgkmcnt(3)
	v_cndmask_b32_e64 v65, v53, -v53, s[6:7]
	s_waitcnt lgkmcnt(2)
	v_cndmask_b32_e64 v67, v55, -v55, s[6:7]
	s_waitcnt lgkmcnt(1)
	v_cndmask_b32_e64 v71, v57, -v57, s[6:7]
	s_waitcnt lgkmcnt(0)
	v_cndmask_b32_e64 v73, v59, -v59, s[6:7]
	v_mul_f32_e32 v44, v238, v61
	v_mul_f32_e32 v46, v239, v63
	v_mul_f32_e32 v48, v240, v65
	v_mul_f32_e32 v50, v241, v67
	v_fma_f32 v44, v32, v242, v44
	v_fma_f32 v45, v33, v243, v46
	v_mul_f32_e32 v52, v238, v71
	v_mul_f32_e32 v40, v239, v73
	v_mul_f32_e32 v54, v240, v75
	v_mul_f32_e32 v42, v241, v77
	v_fma_f32 v46, v34, v244, v48
	v_fma_f32 v47, v35, v245, v50
	v_cndmask_b32_e32 v32, v32, v44, vcc
	v_cndmask_b32_e32 v33, v33, v45, vcc
	v_fma_f32 v48, v36, v242, v52
	v_fma_f32 v40, v37, v243, v40
	v_fma_f32 v41, v38, v244, v54
	v_fma_f32 v42, v39, v245, v42
	v_cndmask_b32_e32 v34, v34, v46, vcc
	v_cndmask_b32_e32 v35, v35, v47, vcc
	v_mul_f32_e32 v32, v87, v32
	v_mul_f32_e32 v33, v87, v33
	v_cndmask_b32_e32 v36, v36, v48, vcc
	v_cndmask_b32_e32 v37, v37, v40, vcc
	v_cndmask_b32_e32 v38, v38, v41, vcc
	v_cndmask_b32_e32 v39, v39, v42, vcc
	v_mul_f32_e32 v34, v87, v34
	v_mul_f32_e32 v35, v87, v35
	v_cvt_pk_bf16_f32 v32, v32, v33
	v_cvt_pk_bf16_f32 v33, v34, v35
	v_mul_f32_e32 v36, v87, v36
	v_mul_f32_e32 v37, v87, v37
	v_mul_f32_e32 v38, v87, v38
	v_mul_f32_e32 v39, v87, v39
	global_store_dwordx2 v[68:69], v[32:33], off offset:8
	v_cvt_pk_bf16_f32 v32, v36, v37
	v_cvt_pk_bf16_f32 v33, v38, v39
	global_store_dwordx2 v[68:69], v[32:33], off offset:264
	v_add_u32_e32 v41, 0xa0, v140
	v_lshlrev_b32_e32 v32, 6, v41
	v_and_b32_e32 v70, 0x3ffc0, v32
	ds_bpermute_b32 v45, v132, v24
	ds_bpermute_b32 v47, v132, v25
	ds_bpermute_b32 v54, v132, v28
	ds_bpermute_b32 v56, v132, v29
	ds_bpermute_b32 v49, v132, v26
	ds_bpermute_b32 v51, v132, v27
	ds_bpermute_b32 v58, v132, v30
	ds_bpermute_b32 v60, v132, v31
	v_mad_i64_i32 v[52:53], s[62:63], s60, v41, 0
	s_waitcnt lgkmcnt(7)
	v_cndmask_b32_e64 v55, v45, -v45, s[6:7]
	s_waitcnt lgkmcnt(6)
	v_cndmask_b32_e64 v57, v47, -v47, s[6:7]
	s_waitcnt lgkmcnt(5)
	v_cndmask_b32_e64 v63, v54, -v54, s[6:7]
	s_waitcnt lgkmcnt(4)
	v_cndmask_b32_e64 v65, v56, -v56, s[6:7]
	s_waitcnt lgkmcnt(3)
	v_cndmask_b32_e64 v59, v49, -v49, s[6:7]
	s_waitcnt lgkmcnt(2)
	v_cndmask_b32_e64 v61, v51, -v51, s[6:7]
	s_waitcnt lgkmcnt(1)
	v_cndmask_b32_e64 v67, v58, -v58, s[6:7]
	s_waitcnt lgkmcnt(0)
	v_cndmask_b32_e64 v69, v60, -v60, s[6:7]
	v_lshl_add_u64 v[52:53], v[52:53], 1, v[144:145]
	s_waitcnt vmcnt(13)
	v_mul_f32_e32 v71, s53, v193
	v_mul_f32_e32 v36, v194, v55
	v_mul_f32_e32 v38, v195, v57
	v_mul_f32_e32 v40, v196, v59
	v_mul_f32_e32 v42, v197, v61
	v_fma_f32 v36, v24, v198, v36
	v_fma_f32 v37, v25, v199, v38
	v_mul_f32_e32 v44, v194, v63
	v_mul_f32_e32 v32, v195, v65
	v_mul_f32_e32 v46, v196, v67
	v_mul_f32_e32 v34, v197, v69
	v_fma_f32 v38, v26, v200, v40
	v_fma_f32 v39, v27, v201, v42
	v_cndmask_b32_e32 v24, v24, v36, vcc
	v_cndmask_b32_e32 v25, v25, v37, vcc
	v_fma_f32 v40, v28, v198, v44
	v_fma_f32 v32, v29, v199, v32
	v_fma_f32 v33, v30, v200, v46
	v_fma_f32 v34, v31, v201, v34
	v_cndmask_b32_e32 v26, v26, v38, vcc
	v_cndmask_b32_e32 v27, v27, v39, vcc
	v_mul_f32_e32 v24, v71, v24
	v_mul_f32_e32 v25, v71, v25
	v_cndmask_b32_e32 v28, v28, v40, vcc
	v_cndmask_b32_e32 v29, v29, v32, vcc
	v_cndmask_b32_e32 v30, v30, v33, vcc
	v_cndmask_b32_e32 v31, v31, v34, vcc
	v_mul_f32_e32 v26, v71, v26
	v_mul_f32_e32 v27, v71, v27
	v_cvt_pk_bf16_f32 v24, v24, v25
	v_cvt_pk_bf16_f32 v25, v26, v27
	v_mul_f32_e32 v28, v71, v28
	v_mul_f32_e32 v29, v71, v29
	v_mul_f32_e32 v30, v71, v30
	v_mul_f32_e32 v31, v71, v31
	global_store_dwordx2 v[52:53], v[24:25], off
	v_cvt_pk_bf16_f32 v24, v28, v29
	v_cvt_pk_bf16_f32 v25, v30, v31
	global_store_dwordx2 v[52:53], v[24:25], off offset:256
	s_nop 0
	ds_bpermute_b32 v33, v132, v16
	ds_bpermute_b32 v35, v132, v17
	ds_bpermute_b32 v44, v132, v22
	ds_bpermute_b32 v46, v132, v23
	ds_bpermute_b32 v37, v132, v18
	ds_bpermute_b32 v39, v132, v19
	ds_bpermute_b32 v41, v132, v20
	ds_bpermute_b32 v43, v132, v21
	s_waitcnt lgkmcnt(7)
	v_cndmask_b32_e64 v45, v33, -v33, s[6:7]
	s_waitcnt lgkmcnt(6)
	v_cndmask_b32_e64 v47, v35, -v35, s[6:7]
	s_waitcnt lgkmcnt(5)
	v_cndmask_b32_e64 v59, v44, -v44, s[6:7]
	s_waitcnt lgkmcnt(4)
	v_cndmask_b32_e64 v61, v46, -v46, s[6:7]
	s_waitcnt lgkmcnt(3)
	v_cndmask_b32_e64 v49, v37, -v37, s[6:7]
	s_waitcnt lgkmcnt(2)
	v_cndmask_b32_e64 v51, v39, -v39, s[6:7]
	s_waitcnt lgkmcnt(1)
	v_cndmask_b32_e64 v55, v41, -v41, s[6:7]
	s_waitcnt lgkmcnt(0)
	v_cndmask_b32_e64 v57, v43, -v43, s[6:7]
	v_mul_f32_e32 v28, v202, v45
	v_mul_f32_e32 v30, v203, v47
	v_mul_f32_e32 v32, v204, v49
	v_mul_f32_e32 v34, v205, v51
	v_fma_f32 v28, v16, v206, v28
	v_fma_f32 v29, v17, v207, v30
	v_mul_f32_e32 v36, v202, v55
	v_mul_f32_e32 v24, v203, v57
	v_mul_f32_e32 v38, v204, v59
	v_mul_f32_e32 v26, v205, v61
	v_fma_f32 v30, v18, v208, v32
	v_fma_f32 v31, v19, v209, v34
	v_cndmask_b32_e32 v16, v16, v28, vcc
	v_cndmask_b32_e32 v17, v17, v29, vcc
	v_fma_f32 v32, v20, v206, v36
	v_fma_f32 v24, v21, v207, v24
	v_fma_f32 v25, v22, v208, v38
	v_fma_f32 v26, v23, v209, v26
	v_cndmask_b32_e32 v18, v18, v30, vcc
	v_cndmask_b32_e32 v19, v19, v31, vcc
	v_mul_f32_e32 v16, v71, v16
	v_mul_f32_e32 v17, v71, v17
	v_cndmask_b32_e32 v20, v20, v32, vcc
	v_cndmask_b32_e32 v21, v21, v24, vcc
	v_cndmask_b32_e32 v22, v22, v25, vcc
	v_cndmask_b32_e32 v23, v23, v26, vcc
	v_mul_f32_e32 v18, v71, v18
	v_mul_f32_e32 v19, v71, v19
	v_cvt_pk_bf16_f32 v16, v16, v17
	v_cvt_pk_bf16_f32 v17, v18, v19
	v_mul_f32_e32 v20, v71, v20
	v_mul_f32_e32 v21, v71, v21
	v_mul_f32_e32 v22, v71, v22
	v_mul_f32_e32 v23, v71, v23
	global_store_dwordx2 v[52:53], v[16:17], off offset:8
	v_cvt_pk_bf16_f32 v16, v20, v21
	v_cvt_pk_bf16_f32 v17, v22, v23
	global_store_dwordx2 v[52:53], v[16:17], off offset:264
	v_add_u32_e32 v25, 0xb0, v140
	v_lshlrev_b32_e32 v16, 6, v25
	v_and_b32_e32 v54, 0x3ffc0, v16
	ds_bpermute_b32 v29, v132, v8
	ds_bpermute_b32 v31, v132, v9
	ds_bpermute_b32 v38, v132, v12
	ds_bpermute_b32 v40, v132, v13
	ds_bpermute_b32 v33, v132, v10
	ds_bpermute_b32 v35, v132, v11
	ds_bpermute_b32 v42, v132, v14
	ds_bpermute_b32 v44, v132, v15
	v_mad_i64_i32 v[36:37], s[60:61], s60, v25, 0
	s_waitcnt lgkmcnt(7)
	v_cndmask_b32_e64 v39, v29, -v29, s[6:7]
	s_waitcnt lgkmcnt(6)
	v_cndmask_b32_e64 v41, v31, -v31, s[6:7]
	s_waitcnt lgkmcnt(5)
	v_cndmask_b32_e64 v47, v38, -v38, s[6:7]
	s_waitcnt lgkmcnt(4)
	v_cndmask_b32_e64 v49, v40, -v40, s[6:7]
	s_waitcnt lgkmcnt(3)
	v_cndmask_b32_e64 v43, v33, -v33, s[6:7]
	s_waitcnt lgkmcnt(2)
	v_cndmask_b32_e64 v45, v35, -v35, s[6:7]
	s_waitcnt lgkmcnt(1)
	v_cndmask_b32_e64 v51, v42, -v42, s[6:7]
	s_waitcnt lgkmcnt(0)
	v_cndmask_b32_e64 v53, v44, -v44, s[6:7]
	v_lshl_add_u64 v[36:37], v[36:37], 1, v[144:145]
	s_waitcnt vmcnt(8)
	v_mul_f32_e32 v55, s53, v211
	v_mul_f32_e32 v20, v212, v39
	v_mul_f32_e32 v22, v213, v41
	v_mul_f32_e32 v24, v214, v43
	v_mul_f32_e32 v26, v215, v45
	v_fma_f32 v20, v8, v216, v20
	v_fma_f32 v21, v9, v217, v22
	v_mul_f32_e32 v28, v212, v47
	v_mul_f32_e32 v16, v213, v49
	v_mul_f32_e32 v30, v214, v51
	v_mul_f32_e32 v18, v215, v53
	v_fma_f32 v22, v10, v218, v24
	v_fma_f32 v23, v11, v219, v26
	v_cndmask_b32_e32 v8, v8, v20, vcc
	v_cndmask_b32_e32 v9, v9, v21, vcc
	v_fma_f32 v24, v12, v216, v28
	v_fma_f32 v16, v13, v217, v16
	v_fma_f32 v17, v14, v218, v30
	v_fma_f32 v18, v15, v219, v18
	v_cndmask_b32_e32 v10, v10, v22, vcc
	v_cndmask_b32_e32 v11, v11, v23, vcc
	v_mul_f32_e32 v8, v55, v8
	v_mul_f32_e32 v9, v55, v9
	v_cndmask_b32_e32 v12, v12, v24, vcc
	v_cndmask_b32_e32 v13, v13, v16, vcc
	v_cndmask_b32_e32 v14, v14, v17, vcc
	v_cndmask_b32_e32 v15, v15, v18, vcc
	v_mul_f32_e32 v10, v55, v10
	v_mul_f32_e32 v11, v55, v11
	v_cvt_pk_bf16_f32 v8, v8, v9
	v_cvt_pk_bf16_f32 v9, v10, v11
	v_mul_f32_e32 v12, v55, v12
	v_mul_f32_e32 v13, v55, v13
	v_mul_f32_e32 v14, v55, v14
	v_mul_f32_e32 v15, v55, v15
	global_store_dwordx2 v[36:37], v[8:9], off
	v_cvt_pk_bf16_f32 v8, v12, v13
	v_cvt_pk_bf16_f32 v9, v14, v15
	global_store_dwordx2 v[36:37], v[8:9], off offset:256
	s_nop 0
	ds_bpermute_b32 v17, v132, v0
	ds_bpermute_b32 v19, v132, v1
	ds_bpermute_b32 v28, v132, v6
	ds_bpermute_b32 v30, v132, v7
	ds_bpermute_b32 v21, v132, v2
	ds_bpermute_b32 v23, v132, v3
	ds_bpermute_b32 v25, v132, v4
	ds_bpermute_b32 v27, v132, v5
	s_waitcnt lgkmcnt(7)
	v_cndmask_b32_e64 v29, v17, -v17, s[6:7]
	s_waitcnt lgkmcnt(6)
	v_cndmask_b32_e64 v31, v19, -v19, s[6:7]
	s_waitcnt lgkmcnt(5)
	v_cndmask_b32_e64 v43, v28, -v28, s[6:7]
	s_waitcnt lgkmcnt(4)
	v_cndmask_b32_e64 v45, v30, -v30, s[6:7]
	s_waitcnt lgkmcnt(3)
	v_cndmask_b32_e64 v33, v21, -v21, s[6:7]
	s_waitcnt lgkmcnt(2)
	v_cndmask_b32_e64 v35, v23, -v23, s[6:7]
	v_mov_b32_e32 v24, v4
	v_mov_b32_e32 v26, v6
	s_waitcnt lgkmcnt(1)
	v_cndmask_b32_e64 v39, v25, -v25, s[6:7]
	s_waitcnt lgkmcnt(0)
	v_cndmask_b32_e64 v41, v27, -v27, s[6:7]
	v_mov_b32_e32 v19, v221
	v_mul_f32_e32 v12, v220, v29
	v_mul_f32_e32 v14, v221, v31
	v_mul_f32_e32 v16, v222, v33
	v_mul_f32_e32 v18, v223, v35
	v_fma_f32 v12, v0, v224, v12
	v_fma_f32 v13, v1, v225, v14
	v_mul_f32_e32 v20, v220, v39
	v_mul_f32_e32 v8, v221, v41
	v_mul_f32_e32 v22, v222, v43
	v_mul_f32_e32 v10, v223, v45
	v_fma_f32 v14, v2, v226, v16
	v_fma_f32 v15, v3, v227, v18
	v_cndmask_b32_e32 v0, v0, v12, vcc
	v_cndmask_b32_e32 v1, v1, v13, vcc
	v_fma_f32 v16, v4, v224, v20
	v_fma_f32 v8, v5, v225, v8
	v_fma_f32 v9, v6, v226, v22
	v_fma_f32 v10, v7, v227, v10
	v_cndmask_b32_e32 v2, v2, v14, vcc
	v_cndmask_b32_e32 v3, v3, v15, vcc
	v_mul_f32_e32 v0, v55, v0
	v_mul_f32_e32 v1, v55, v1
	v_cndmask_b32_e32 v4, v4, v16, vcc
	v_cndmask_b32_e32 v5, v5, v8, vcc
	v_cndmask_b32_e32 v6, v6, v9, vcc
	v_cndmask_b32_e32 v7, v7, v10, vcc
	v_mul_f32_e32 v2, v55, v2
	v_mul_f32_e32 v3, v55, v3
	v_cvt_pk_bf16_f32 v0, v0, v1
	v_cvt_pk_bf16_f32 v1, v2, v3
	v_mul_f32_e32 v4, v55, v4
	v_mul_f32_e32 v5, v55, v5
	v_mul_f32_e32 v6, v55, v6
	v_mul_f32_e32 v7, v55, v7
	global_store_dwordx2 v[36:37], v[0:1], off offset:8
	v_cvt_pk_bf16_f32 v0, v4, v5
	v_cvt_pk_bf16_f32 v1, v6, v7
	global_store_dwordx2 v[36:37], v[0:1], off offset:264
